# v95 plus nt hint on the last-use bf16 row loads of the final RMSNorm phase
# baseline (speedup 1.0000x reference)
; __device__ __forceinline__ void final_rows(const bf16_t* XB, float* out, const float* g, const float* SS, int gw, int NGW, int lane) {
;     ...
;         u32x2 w[4][4]; float tp[4];
; #pragma unroll
;         for (int q = 0; q < 4; ++q) { const u32x2* xr = (const u32x2*)(XB + (size_t)(m0 + q) * D) + lane;
; #pragma unroll
;             for (int j = 0; j < 4; ++j) w[q][j] = xr[64 * j];
;             tp[q] = (lane < 16) ? SS[(size_t)lane * T + m0 + q] : 0.f; }
.LBB0_1906:
	v_lshl_add_u64 v[22:23], s[28:29], 0, v[18:19]
	v_add_co_u32_e32 v24, vcc, 0x6800000, v22
	v_lshl_add_u64 v[54:55], s[28:29], 0, v[20:21]
	s_nop 0
	v_addc_co_u32_e32 v25, vcc, 0, v23, vcc
	global_load_dwordx2 v[52:53], v[24:25], off nt
	global_load_dwordx2 v[50:51], v[24:25], off offset:512 nt
	global_load_dwordx2 v[48:49], v[24:25], off offset:1024 nt
	global_load_dwordx2 v[46:47], v[24:25], off offset:1536 nt
	v_mov_b32_e32 v66, 0
	s_and_saveexec_b64 s[2:3], s[0:1]
	s_cbranch_execz .LBB0_1908
	v_add_co_u32_e32 v24, vcc, 0x6400000, v54
	s_nop 1
	v_addc_co_u32_e32 v25, vcc, 0, v55, vcc
	global_load_dword v66, v[24:25], off
.LBB0_1908:
	s_or_b64 exec, exec, s[2:3]
	v_add_co_u32_e32 v24, vcc, 0x6800000, v22
	v_mov_b32_e32 v64, 0
	s_nop 0
	v_addc_co_u32_e32 v25, vcc, 0, v23, vcc
	global_load_dwordx2 v[44:45], v[24:25], off offset:2048 nt
	global_load_dwordx2 v[42:43], v[24:25], off offset:2560 nt
	global_load_dwordx2 v[40:41], v[24:25], off offset:3072 nt
	global_load_dwordx2 v[38:39], v[24:25], off offset:3584 nt
	v_mov_b32_e32 v65, 0
	s_and_saveexec_b64 s[2:3], s[0:1]
	s_cbranch_execz .LBB0_1910
	v_add_co_u32_e32 v24, vcc, 0x6400000, v54
	s_nop 1
	v_addc_co_u32_e32 v25, vcc, 0, v55, vcc
	global_load_dword v65, v[24:25], off offset:4
.LBB0_1910:
	s_or_b64 exec, exec, s[2:3]
	v_add_co_u32_e32 v24, vcc, 0x6801000, v22
	s_nop 1
	v_addc_co_u32_e32 v25, vcc, 0, v23, vcc
	global_load_dwordx2 v[36:37], v[24:25], off nt
	global_load_dwordx2 v[34:35], v[24:25], off offset:512 nt
	global_load_dwordx2 v[32:33], v[24:25], off offset:1024 nt
	global_load_dwordx2 v[30:31], v[24:25], off offset:1536 nt
	s_and_saveexec_b64 s[2:3], s[0:1]
	s_cbranch_execz .LBB0_1912
	v_add_co_u32_e32 v24, vcc, 0x6400000, v54
	s_nop 1
	v_addc_co_u32_e32 v25, vcc, 0, v55, vcc
	global_load_dword v64, v[24:25], off offset:8
.LBB0_1912:
	s_or_b64 exec, exec, s[2:3]
	v_add_co_u32_e32 v68, vcc, 0x6801000, v22
	v_mov_b32_e32 v63, 0
	s_nop 0
	v_addc_co_u32_e32 v69, vcc, 0, v23, vcc
	global_load_dwordx2 v[28:29], v[68:69], off offset:2048 nt
	global_load_dwordx2 v[26:27], v[68:69], off offset:2560 nt
	global_load_dwordx2 v[24:25], v[68:69], off offset:3072 nt
	global_load_dwordx2 v[22:23], v[68:69], off offset:3584 nt
	s_and_saveexec_b64 s[2:3], s[0:1]
	s_cbranch_execz .LBB0_1905
	v_add_co_u32_e32 v54, vcc, 0x6400000, v54
	s_nop 1
	v_addc_co_u32_e32 v55, vcc, 0, v55, vcc
	global_load_dword v63, v[54:55], off offset:12
	s_branch .LBB0_1905
